# slot-1 weight conversion moved from the input-projection phase into the first gate/up phase's idle tail (same workgroups, right after their slot-0 conversion)
# speedup vs baseline: 1.0162x; 1.0113x over previous
; __global__ void __launch_bounds__(NWAVES * 64, 2) fwd_kernel(Args a) {
;     ...
;                 IDLE_CONVERT(f ? 2 : 0);
.Lconv_sig_done:
	s_mov_b64 exec, s[28:29]
	v_readlane_b32 s4, v252, 23
	s_nop 3
	s_cmp_lg_u32 s4, 0
	s_cbranch_scc1 .LBB0_387
	s_cmpk_lg_i32 s70, 0x100
	s_cbranch_scc1 .LBB0_387
	s_branch .Lc1_entry

.Ls2_done:
.LBB0_874:
	s_cmpk_eq_i32 s70, 0x100
	s_cbranch_scc1 .LBB0_1022
	v_readlane_b32 s4, v253, 6
	v_readlane_b32 s5, v253, 7
	s_andn2_b64 vcc, exec, s[4:5]
	s_cbranch_vccnz .LBB0_1022
.Lc1_entry:
	v_mov_b32_e32 v0, v210
	s_mov_b64 s[28:29], -1
	v_readfirstlane_b32 s4, v0
	v_and_b32_e32 v141, 63, v0
	s_ashr_i32 s7, s4, 6
	v_readlane_b32 s4, v253, 8
	v_lshlrev_b32_e32 v2, 2, v141
	s_add_i32 s4, s7, s4
	s_cmpk_lt_i32 s4, 0x100
	v_lshrrev_b32_e32 v130, 4, v141
	v_and_b32_e32 v132, 60, v2
	s_movk_i32 s19, 0xb00
	s_cbranch_scc1 .LBB0_877
	v_lshrrev_b32_e32 v0, 4, v141
	v_and_b32_e32 v66, 60, v2
	v_mov_b32_e32 v67, v1
	s_mov_b64 s[28:29], 0
	v_mov_b64_e32 v[134:135], v[66:67]
	v_mov_b64_e32 v[136:137], v[0:1]

.LBB0_1021:
	s_barrier
	s_cmpk_eq_i32 s70, 0x100
	s_cbranch_scc1 .LBB0_387
